# branch A peeled last group: batch 8 A-fragment ds_reads after barrier (same as loop body)
# speedup vs baseline: 1.0213x; 1.0083x over previous
; __device__ __forceinline__ u32x4 pack8(const f32x4 a, const f32x4 b) { u32x4 w; w.x = cvt_pk_bf16(a[0], a[1]); w.y = cvt_pk_bf16(a[2], a[3]); w.z = cvt_pk_bf16(b[0], b[1]); w.w = cvt_pk_bf16(b[2], b[3]); return w; }
; #define LAS __attribute__((address_space(3)))
;     ...
; #pragma unroll
;         for (int i = 0; i < 4; ++i) {
;             const int p = tid + 512 * i, s = p >> 4, dc = p & 15;
;             f32x4 v0, v1; pg8::unpack8(vpc[i], v0, v1);
;             const float mean = stat[s * 2], rstd = stat[s * 2 + 1];
;             v0 = (v0 - mean) * rstd * ga + ba; v1 = (v1 - mean) * rstd * gb2 + bb2;
;             const u32x4 w = pg8::pack8(v0, v1);
;             LAS unsigned short* dst = (LAS unsigned short*)(lds + BA_VNT) + dc * 136 + s;
;             dst[0 * 16 * 136] = (unsigned short)(w.x & 0xffffu); dst[1 * 16 * 136] = (unsigned short)(w.x >> 16); dst[2 * 16 * 136] = (unsigned short)(w.y & 0xffffu); dst[3 * 16 * 136] = (unsigned short)(w.y >> 16);
;             dst[4 * 16 * 136] = (unsigned short)(w.z & 0xffffu); dst[5 * 16 * 136] = (unsigned short)(w.z >> 16); dst[6 * 16 * 136] = (unsigned short)(w.w & 0xffffu); dst[7 * 16 * 136] = (unsigned short)(w.w >> 16);
;         }
;         if (g + 1 < 8) {
; #pragma unroll
;             for (int i = 0; i < 4; ++i) { const int p = tid + 512 * i, s = p >> 4, dc = p & 15; vpc[i] = *(const u32x4*)(Vb + (t0 + s) * 1024 + (g + 1) * 128 + dc * 8); }
;         }
;         __syncthreads();
;         const int d = 32 * dblk + r32;
;         const LAS unsigned char* ab = lds + BA_VNT + ((d & 7) * 16 + (d >> 3)) * 272 + hi * 16;
;         f32x16 acc[2];
; #pragma unroll
;         for (int j = 0; j < 2; ++j) {
;             const int tb = 2 * tbp + j;
; #pragma unroll
;             for (int r = 0; r < 16; ++r) acc[j][r] = 0.f;
; #pragma unroll
;             for (int ks = 0; ks < 8; ++ks) if (ks < 2 * (tb + 1)) {
;                 const bf16x8 af = *(const LAS bf16x8*)(ab + ks * 32);
;                 acc[j] = __builtin_amdgcn_mfma_f32_32x32x16_bf16(af, wf[j][ks], acc[j], 0, 0, 0);
;             }
.LBB0_574:
	s_waitcnt vmcnt(8)
	ds_read_b128 v[8:11], v175 offset:4608
	ds_read_b128 v[0:3], v175 offset:4624
	ds_read_b128 v[12:15], v175 offset:8704
	ds_read_b128 v[4:7], v175 offset:8720
	ds_read_b64 v[16:17], v177
	v_lshlrev_b32_e32 v20, 16, v126
	v_and_b32_e32 v21, 0xffff0000, v126
	v_lshlrev_b32_e32 v18, 16, v127
	v_and_b32_e32 v19, 0xffff0000, v127
	v_lshlrev_b32_e32 v24, 16, v128
	v_and_b32_e32 v25, 0xffff0000, v128
	v_lshlrev_b32_e32 v22, 16, v129
	v_and_b32_e32 v23, 0xffff0000, v129
	s_waitcnt lgkmcnt(0)
	v_sub_f32_e32 v21, v21, v16
	v_sub_f32_e32 v20, v20, v16
	v_sub_f32_e32 v19, v19, v16
	v_sub_f32_e32 v18, v18, v16
	v_pk_mul_f32 v[20:21], v[16:17], v[20:21] op_sel:[1,0]
	v_sub_f32_e32 v23, v23, v16
	v_sub_f32_e32 v22, v22, v16
	v_sub_f32_e32 v25, v25, v16
	v_sub_f32_e32 v24, v24, v16
	v_pk_mul_f32 v[18:19], v[16:17], v[18:19] op_sel:[1,0]
	v_pk_fma_f32 v[20:21], v[8:9], v[20:21], v[12:13]
	v_pk_mul_f32 v[24:25], v[16:17], v[24:25] op_sel:[1,0]
	v_pk_mul_f32 v[16:17], v[16:17], v[22:23] op_sel:[1,0]
	v_pk_fma_f32 v[18:19], v[10:11], v[18:19], v[14:15]
	v_pk_fma_f32 v[16:17], v[2:3], v[16:17], v[6:7]
	v_pk_fma_f32 v[22:23], v[0:1], v[24:25], v[4:5]
	v_cvt_pk_bf16_f32 v20, v20, v21
	v_cvt_pk_bf16_f32 v18, v18, v19
	v_cvt_pk_bf16_f32 v19, v22, v23
	v_cvt_pk_bf16_f32 v16, v16, v17
	ds_write_b16 v174, v20 offset:9216
	ds_write_b16_d16_hi v174, v20 offset:13568
	ds_write_b16 v174, v18 offset:17920
	ds_write_b16_d16_hi v174, v18 offset:22272
	ds_write_b16 v174, v19 offset:26624
	ds_write_b16_d16_hi v174, v19 offset:30976
	ds_write_b16 v174, v16 offset:35328
	ds_write_b16_d16_hi v174, v16 offset:39680
	ds_read_b64 v[16:17], v173
	v_lshlrev_b32_e32 v20, 16, v122
	v_and_b32_e32 v21, 0xffff0000, v122
	v_lshlrev_b32_e32 v18, 16, v123
	v_and_b32_e32 v19, 0xffff0000, v123
	v_lshlrev_b32_e32 v24, 16, v124
	v_and_b32_e32 v25, 0xffff0000, v124
	v_lshlrev_b32_e32 v22, 16, v125
	v_and_b32_e32 v23, 0xffff0000, v125
	s_waitcnt lgkmcnt(0)
	v_sub_f32_e32 v21, v21, v16
	v_sub_f32_e32 v20, v20, v16
	v_sub_f32_e32 v19, v19, v16
	v_sub_f32_e32 v18, v18, v16
	v_pk_mul_f32 v[20:21], v[16:17], v[20:21] op_sel:[1,0]
	v_sub_f32_e32 v23, v23, v16
	v_sub_f32_e32 v22, v22, v16
	v_sub_f32_e32 v25, v25, v16
	v_sub_f32_e32 v24, v24, v16
	v_pk_mul_f32 v[18:19], v[16:17], v[18:19] op_sel:[1,0]
	v_pk_fma_f32 v[20:21], v[8:9], v[20:21], v[12:13]
	v_pk_mul_f32 v[24:25], v[16:17], v[24:25] op_sel:[1,0]
	v_pk_mul_f32 v[16:17], v[16:17], v[22:23] op_sel:[1,0]
	v_pk_fma_f32 v[18:19], v[10:11], v[18:19], v[14:15]
	v_pk_fma_f32 v[16:17], v[2:3], v[16:17], v[6:7]
	v_pk_fma_f32 v[22:23], v[0:1], v[24:25], v[4:5]
	v_cvt_pk_bf16_f32 v20, v20, v21
	v_cvt_pk_bf16_f32 v18, v18, v19
	v_cvt_pk_bf16_f32 v19, v22, v23
	v_cvt_pk_bf16_f32 v16, v16, v17
	ds_write_b16 v172, v20 offset:9216
	ds_write_b16_d16_hi v172, v20 offset:13568
	ds_write_b16 v172, v18 offset:17920
	ds_write_b16_d16_hi v172, v18 offset:22272
	ds_write_b16 v172, v19 offset:26624
	ds_write_b16_d16_hi v172, v19 offset:30976
	ds_write_b16 v172, v16 offset:35328
	ds_write_b16_d16_hi v172, v16 offset:39680
	ds_read_b64 v[16:17], v171
	v_lshlrev_b32_e32 v20, 16, v118
	v_and_b32_e32 v21, 0xffff0000, v118
	v_lshlrev_b32_e32 v18, 16, v119
	v_and_b32_e32 v19, 0xffff0000, v119
	v_lshlrev_b32_e32 v24, 16, v120
	v_and_b32_e32 v25, 0xffff0000, v120
	v_lshlrev_b32_e32 v22, 16, v121
	v_and_b32_e32 v23, 0xffff0000, v121
	s_waitcnt lgkmcnt(0)
	v_sub_f32_e32 v21, v21, v16
	v_sub_f32_e32 v20, v20, v16
	v_sub_f32_e32 v19, v19, v16
	v_sub_f32_e32 v18, v18, v16
	v_pk_mul_f32 v[20:21], v[16:17], v[20:21] op_sel:[1,0]
	v_sub_f32_e32 v23, v23, v16
	v_sub_f32_e32 v22, v22, v16
	v_sub_f32_e32 v25, v25, v16
	v_sub_f32_e32 v24, v24, v16
	v_pk_mul_f32 v[18:19], v[16:17], v[18:19] op_sel:[1,0]
	v_pk_fma_f32 v[20:21], v[8:9], v[20:21], v[12:13]
	v_pk_mul_f32 v[24:25], v[16:17], v[24:25] op_sel:[1,0]
	v_pk_mul_f32 v[16:17], v[16:17], v[22:23] op_sel:[1,0]
	v_pk_fma_f32 v[18:19], v[10:11], v[18:19], v[14:15]
	v_pk_fma_f32 v[16:17], v[2:3], v[16:17], v[6:7]
	v_pk_fma_f32 v[22:23], v[0:1], v[24:25], v[4:5]
	v_cvt_pk_bf16_f32 v20, v20, v21
	v_cvt_pk_bf16_f32 v18, v18, v19
	v_cvt_pk_bf16_f32 v19, v22, v23
	v_cvt_pk_bf16_f32 v16, v16, v17
	ds_write_b16 v170, v20 offset:9216
	ds_write_b16_d16_hi v170, v20 offset:13568
	ds_write_b16 v170, v18 offset:17920
	ds_write_b16_d16_hi v170, v18 offset:22272
	ds_write_b16 v170, v19 offset:26624
	ds_write_b16_d16_hi v170, v19 offset:30976
	ds_write_b16 v170, v16 offset:35328
	ds_write_b16_d16_hi v170, v16 offset:39680
	ds_read_b64 v[16:17], v169
	v_lshlrev_b32_e32 v20, 16, v114
	v_and_b32_e32 v21, 0xffff0000, v114
	v_lshlrev_b32_e32 v18, 16, v115
	v_and_b32_e32 v19, 0xffff0000, v115
	s_waitcnt lgkmcnt(0)
	v_sub_f32_e32 v19, v19, v16
	v_sub_f32_e32 v18, v18, v16
	v_sub_f32_e32 v21, v21, v16
	v_sub_f32_e32 v20, v20, v16
	v_lshlrev_b32_e32 v22, 16, v116
	v_and_b32_e32 v23, 0xffff0000, v116
	v_lshlrev_b32_e32 v24, 16, v117
	v_and_b32_e32 v25, 0xffff0000, v117
	v_pk_mul_f32 v[20:21], v[16:17], v[20:21] op_sel:[1,0]
	v_pk_mul_f32 v[18:19], v[16:17], v[18:19] op_sel:[1,0]
	v_pk_fma_f32 v[8:9], v[8:9], v[20:21], v[12:13]
	v_pk_fma_f32 v[10:11], v[10:11], v[18:19], v[14:15]
	v_sub_f32_e32 v13, v25, v16
	v_sub_f32_e32 v12, v24, v16
	v_sub_f32_e32 v15, v23, v16
	v_sub_f32_e32 v14, v22, v16
	v_pk_mul_f32 v[14:15], v[16:17], v[14:15] op_sel:[1,0]
	v_pk_mul_f32 v[12:13], v[16:17], v[12:13] op_sel:[1,0]
	v_pk_fma_f32 v[0:1], v[0:1], v[14:15], v[4:5]
	v_pk_fma_f32 v[2:3], v[2:3], v[12:13], v[6:7]
	v_cvt_pk_bf16_f32 v4, v8, v9
	s_and_b64 vcc, exec, s[38:39]
	v_add_u32_e32 v64, v139, v140
	v_cvt_pk_bf16_f32 v5, v10, v11
	v_cvt_pk_bf16_f32 v0, v0, v1
	v_cvt_pk_bf16_f32 v1, v2, v3
	ds_write_b16 v168, v4 offset:9216
	ds_write_b16_d16_hi v168, v4 offset:13568
	ds_write_b16 v168, v5 offset:17920
	ds_write_b16_d16_hi v168, v5 offset:22272
	ds_write_b16 v168, v0 offset:26624
	ds_write_b16_d16_hi v168, v0 offset:30976
	ds_write_b16 v168, v1 offset:35328
	ds_write_b16_d16_hi v168, v1 offset:39680
	s_waitcnt lgkmcnt(0)
	s_barrier
	ds_read_b128 v[206:209], v64 offset:9216
	ds_read_b128 v[210:213], v64 offset:9248
	ds_read_b128 v[214:217], v64 offset:9280
	ds_read_b128 v[218:221], v64 offset:9312
	ds_read_b128 v[222:225], v64 offset:9344
	ds_read_b128 v[226:229], v64 offset:9376
	ds_read_b128 v[242:245], v64 offset:9408
	ds_read_b128 v[246:249], v64 offset:9440
	s_waitcnt lgkmcnt(0)
	s_cbranch_vccnz .LBB0_605
	v_mfma_f32_32x32x16_bf16 v[0:15], v[206:209], v[110:113], 0
	s_and_b64 vcc, exec, s[38:39]
	s_cbranch_vccnz .LBB0_577
.LBB0_576:
	v_mfma_f32_32x32x16_bf16 v[0:15], v[210:213], v[106:109], v[0:15]

; #define LAS __attribute__((address_space(3)))
;     ...
;             for (int ks = 0; ks < 8; ++ks) if (ks < 2 * (tb + 1)) {
;                 const bf16x8 af = *(const LAS bf16x8*)(ab + ks * 32);
;                 acc[j] = __builtin_amdgcn_mfma_f32_32x32x16_bf16(af, wf[j][ks], acc[j], 0, 0, 0);
.LBB0_579:
	s_and_b64 vcc, exec, s[40:41]
	s_cbranch_vccnz .LBB0_581
	v_mfma_f32_32x32x16_bf16 v[0:15], v[218:221], v[98:101], v[0:15]

; #define LAS __attribute__((address_space(3)))
;     ...
;             for (int ks = 0; ks < 8; ++ks) if (ks < 2 * (tb + 1)) {
;                 const bf16x8 af = *(const LAS bf16x8*)(ab + ks * 32);
;                 acc[j] = __builtin_amdgcn_mfma_f32_32x32x16_bf16(af, wf[j][ks], acc[j], 0, 0, 0);
.LBB0_583:
	s_and_b64 vcc, exec, s[42:43]
	s_cbranch_vccnz .LBB0_588
	v_mfma_f32_32x32x16_bf16 v[0:15], v[226:229], v[90:93], v[0:15]
	s_and_b64 vcc, exec, s[44:45]
	s_cbranch_vccz .LBB0_589
.LBB0_585:
	s_and_b64 vcc, exec, s[46:47]
	s_cbranch_vccnz .LBB0_590
.LBB0_586:
	v_mfma_f32_32x32x16_bf16 v[0:15], v[246:249], v[82:85], v[0:15]
	s_and_b64 vcc, exec, s[38:39]
	s_cbranch_vccz .LBB0_591

; #define LAS __attribute__((address_space(3)))
;     ...
;             for (int ks = 0; ks < 8; ++ks) if (ks < 2 * (tb + 1)) {
;                 const bf16x8 af = *(const LAS bf16x8*)(ab + ks * 32);
;                 acc[j] = __builtin_amdgcn_mfma_f32_32x32x16_bf16(af, wf[j][ks], acc[j], 0, 0, 0);
.LBB0_589:
	v_mfma_f32_32x32x16_bf16 v[0:15], v[242:245], v[86:89], v[0:15]
	s_and_b64 vcc, exec, s[46:47]
	s_cbranch_vccz .LBB0_586

; #define LAS __attribute__((address_space(3)))
;     ...
;             for (int ks = 0; ks < 8; ++ks) if (ks < 2 * (tb + 1)) {
;                 const bf16x8 af = *(const LAS bf16x8*)(ab + ks * 32);
;                 acc[j] = __builtin_amdgcn_mfma_f32_32x32x16_bf16(af, wf[j][ks], acc[j], 0, 0, 0);
.LBB0_603:
	s_and_b64 vcc, exec, s[36:37]
	s_cbranch_vccnz .LBB0_473
	v_mfma_f32_32x32x16_bf16 v[16:31], v[246:249], v[40:43], v[16:31]
	s_branch .LBB0_473
